# attention steady loop: the two canonicalizing v_max x,x after each v_permlane32_swap on the serial max->branch chain deleted (placement of later loops kept by padding); on top of P4 split + carry move
# speedup vs baseline: 1.0040x; 1.0005x over previous
.LBB0_563:
	v_add_u32_e32 v0, s12, v194
	ds_read_b64_tr_b16 v[168:169], v0 offset:24576
	ds_read_b64_tr_b16 v[170:171], v0 offset:25088
	s_waitcnt lgkmcnt(5)
	v_mfma_f32_32x32x16_bf16 v[112:127], v[164:167], v[144:147], v[48:63]
	v_add_f32_e32 v2, v80, v81
	v_add_f32_e32 v2, v82, v2
	v_add_f32_e32 v2, v83, v2
	v_add_f32_e32 v2, v84, v2
	v_add_f32_e32 v2, v85, v2
	v_cvt_pk_bf16_f32 v148, v80, v81
	v_cvt_pk_bf16_f32 v149, v82, v83
	ds_read_b64_tr_b16 v[164:165], v0 offset:28672
	ds_read_b64_tr_b16 v[166:167], v0 offset:29184
	s_waitcnt lgkmcnt(6)
	v_mfma_f32_32x32x16_bf16 v[96:111], v[160:163], v[144:147], v[48:63]
	v_add_f32_e32 v2, v86, v2
	v_add_f32_e32 v2, v87, v2
	v_add_f32_e32 v2, v88, v2
	v_add_f32_e32 v2, v89, v2
	v_cvt_pk_bf16_f32 v150, v84, v85
	v_cvt_pk_bf16_f32 v151, v86, v87
	ds_read_b64_tr_b16 v[6:7], v0 offset:25600
	ds_read_b64_tr_b16 v[8:9], v0 offset:26112
	s_waitcnt lgkmcnt(7)
	v_mfma_f32_32x32x16_bf16 v[112:127], v[156:159], v[136:139], v[112:127]
	v_add_f32_e32 v2, v90, v2
	v_add_f32_e32 v2, v91, v2
	v_add_f32_e32 v2, v92, v2
	v_add_f32_e32 v2, v93, v2
	v_cvt_pk_bf16_f32 v140, v88, v89
	v_cvt_pk_bf16_f32 v141, v90, v91
	ds_read_b64_tr_b16 v[80:81], v0 offset:29696
	ds_read_b64_tr_b16 v[82:83], v0 offset:30208
	s_waitcnt lgkmcnt(8)
	v_mfma_f32_32x32x16_bf16 v[96:111], v[152:155], v[136:139], v[96:111]
	v_add_f32_e32 v2, v94, v2
	v_add_f32_e32 v2, v95, v2
	v_add_f32_e32 v2, v64, v2
	v_add_f32_e32 v2, v65, v2
	v_cvt_pk_bf16_f32 v142, v92, v93
	v_cvt_pk_bf16_f32 v143, v94, v95
	ds_read_b64_tr_b16 v[84:85], v0 offset:26624
	ds_read_b64_tr_b16 v[86:87], v0 offset:27136
	v_add_f32_e32 v2, v66, v2
	v_add_f32_e32 v2, v67, v2
	v_add_f32_e32 v2, v68, v2
	v_add_f32_e32 v2, v69, v2
	v_cvt_pk_bf16_f32 v132, v64, v65
	v_cvt_pk_bf16_f32 v133, v66, v67
	ds_read_b64_tr_b16 v[64:65], v0 offset:30720
	ds_read_b64_tr_b16 v[66:67], v0 offset:31232
	v_add_f32_e32 v2, v70, v2
	v_add_f32_e32 v2, v71, v2
	v_add_f32_e32 v2, v72, v2
	v_add_f32_e32 v2, v73, v2
	v_cvt_pk_bf16_f32 v134, v68, v69
	v_cvt_pk_bf16_f32 v135, v70, v71
	ds_read_b64_tr_b16 v[10:11], v0 offset:27648
	ds_read_b64_tr_b16 v[12:13], v0 offset:28160
	v_add_f32_e32 v2, v74, v2
	v_add_f32_e32 v2, v75, v2
	v_add_f32_e32 v2, v76, v2
	v_add_f32_e32 v14, v77, v2
	v_cvt_pk_bf16_f32 v128, v72, v73
	v_cvt_pk_bf16_f32 v129, v74, v75
	ds_read_b64_tr_b16 v[2:3], v0 offset:31744
	ds_read_b64_tr_b16 v[4:5], v0 offset:32256
	v_add_f32_e32 v0, v78, v14
	v_add_f32_e32 v0, v79, v0
	v_add_f32_e32 v0, 0, v0
	v_cvt_pk_bf16_f32 v130, v76, v77
	v_cvt_pk_bf16_f32 v131, v78, v79
	v_lshl_add_u64 v[14:15], v[178:179], 0, s[50:51]
	s_add_i32 s12, s3, s75
	s_mov_b32 s13, m0
	s_mov_b32 m0, s12
	s_nop 0
	global_load_lds_dwordx4 v[14:15], off
	s_mov_b32 m0, s13
	s_mov_b32 s12, 0xfffb0000
	s_mov_b32 s13, -1
	v_lshl_add_u64 v[14:15], v[176:177], 0, s[12:13]
	s_add_i32 s12, s16, s76
	s_mov_b32 s13, m0
	s_mov_b32 m0, s12
	s_nop 0
	global_load_lds_dwordx4 v[14:15], off
	s_mov_b32 m0, s13
	v_max_f32_e32 v14, v113, v113
	v_max_f32_e32 v15, v112, v112
	v_max_f32_e32 v14, v15, v14
	v_max3_f32 v15, v114, v115, v97
	v_max3_f32 v14, v14, v96, v98
	v_max3_f32 v14, v14, v99, v116
	v_max3_f32 v15, v15, v118, v119
	v_max3_f32 v14, v14, v117, v100
	v_max3_f32 v15, v15, v102, v103
	v_max3_f32 v14, v14, v101, v120
	v_max3_f32 v15, v15, v122, v123
	v_max3_f32 v14, v14, v121, v104
	v_max3_f32 v15, v15, v106, v107
	v_max3_f32 v14, v14, v105, v124
	v_max3_f32 v15, v15, v126, v127
	v_max3_f32 v68, v14, v125, v108
	v_max3_f32 v15, v15, v110, v111
	v_add_f32_e32 v14, v196, v0
	v_max3_f32 v0, v68, v109, v15
	v_mov_b32_e32 v15, v0
	s_nop 1
	v_permlane32_swap_b32_e32 v0, v15
	v_max_f32_e32 v0, v0, v15
	v_cmp_lt_f32_e32 vcc, s58, v0
	s_cmp_lg_u64 vcc, 0
	s_cselect_b64 s[12:13], -1, 0
	s_cbranch_vccnz .LBB0_571

.LBB0_566:
	s_add_i32 s12, s16, 0x2000
	s_cmpk_lg_i32 s16, 0x4000
	s_cselect_b32 s78, s12, 0
	v_add_u32_e32 v4, s3, v194
	ds_read_b64_tr_b16 v[156:157], v4 offset:24576
	ds_read_b64_tr_b16 v[158:159], v4 offset:25088
	s_waitcnt lgkmcnt(5)
	v_mfma_f32_32x32x16_bf16 v[80:95], v[68:71], v[144:147], v[48:63]
	v_add_f32_e32 v2, v112, v113
	v_add_f32_e32 v2, v114, v2
	v_add_f32_e32 v2, v115, v2
	v_add_f32_e32 v2, v116, v2
	v_add_f32_e32 v2, v117, v2
	v_cvt_pk_bf16_f32 v148, v112, v113
	v_cvt_pk_bf16_f32 v149, v114, v115
	ds_read_b64_tr_b16 v[152:153], v4 offset:28672
	ds_read_b64_tr_b16 v[154:155], v4 offset:29184
	s_waitcnt lgkmcnt(6)
	v_mfma_f32_32x32x16_bf16 v[64:79], v[164:167], v[144:147], v[48:63]
	v_add_f32_e32 v2, v118, v2
	v_add_f32_e32 v2, v119, v2
	v_add_f32_e32 v2, v120, v2
	v_add_f32_e32 v2, v121, v2
	v_cvt_pk_bf16_f32 v150, v116, v117
	v_cvt_pk_bf16_f32 v151, v118, v119
	ds_read_b64_tr_b16 v[6:7], v4 offset:25600
	ds_read_b64_tr_b16 v[8:9], v4 offset:26112
	s_waitcnt lgkmcnt(7)
	v_mfma_f32_32x32x16_bf16 v[80:95], v[168:171], v[136:139], v[80:95]
	v_add_f32_e32 v2, v122, v2
	v_add_f32_e32 v2, v123, v2
	v_add_f32_e32 v2, v124, v2
	v_add_f32_e32 v2, v125, v2
	v_cvt_pk_bf16_f32 v140, v120, v121
	v_cvt_pk_bf16_f32 v141, v122, v123
	ds_read_b64_tr_b16 v[112:113], v4 offset:29696
	ds_read_b64_tr_b16 v[114:115], v4 offset:30208
	s_waitcnt lgkmcnt(8)
	v_mfma_f32_32x32x16_bf16 v[64:79], v[160:163], v[136:139], v[64:79]
	v_add_f32_e32 v2, v126, v2
	v_add_f32_e32 v2, v127, v2
	v_add_f32_e32 v2, v96, v2
	v_add_f32_e32 v2, v97, v2
	v_cvt_pk_bf16_f32 v142, v124, v125
	v_cvt_pk_bf16_f32 v143, v126, v127
	ds_read_b64_tr_b16 v[116:117], v4 offset:26624
	ds_read_b64_tr_b16 v[118:119], v4 offset:27136
	v_add_f32_e32 v2, v98, v2
	v_add_f32_e32 v2, v99, v2
	v_add_f32_e32 v2, v100, v2
	v_add_f32_e32 v2, v101, v2
	v_cvt_pk_bf16_f32 v132, v96, v97
	v_cvt_pk_bf16_f32 v133, v98, v99
	ds_read_b64_tr_b16 v[96:97], v4 offset:30720
	ds_read_b64_tr_b16 v[98:99], v4 offset:31232
	v_add_f32_e32 v2, v102, v2
	v_add_f32_e32 v2, v103, v2
	v_add_f32_e32 v2, v104, v2
	v_add_f32_e32 v2, v105, v2
	v_cvt_pk_bf16_f32 v134, v100, v101
	v_cvt_pk_bf16_f32 v135, v102, v103
	ds_read_b64_tr_b16 v[10:11], v4 offset:27648
	ds_read_b64_tr_b16 v[12:13], v4 offset:28160
	v_add_f32_e32 v2, v106, v2
	v_add_f32_e32 v2, v107, v2
	v_add_f32_e32 v2, v108, v2
	v_add_f32_e32 v15, v109, v2
	v_cvt_pk_bf16_f32 v128, v104, v105
	v_cvt_pk_bf16_f32 v129, v106, v107
	ds_read_b64_tr_b16 v[2:3], v4 offset:31744
	ds_read_b64_tr_b16 v[4:5], v4 offset:32256
	v_add_f32_e32 v15, v110, v15
	v_add_f32_e32 v15, v111, v15
	v_add_f32_e32 v15, 0, v15
	v_cvt_pk_bf16_f32 v130, v108, v109
	v_cvt_pk_bf16_f32 v131, v110, v111
	v_max_f32_e32 v100, v81, v81
	v_max_f32_e32 v101, v80, v80
	v_max_f32_e32 v100, v101, v100
	v_max3_f32 v101, v82, v83, v65
	v_max3_f32 v100, v100, v64, v66
	v_max3_f32 v100, v100, v67, v84
	v_max3_f32 v101, v101, v86, v87
	v_max3_f32 v100, v100, v85, v68
	v_max3_f32 v101, v101, v70, v71
	v_max3_f32 v100, v100, v69, v88
	v_max3_f32 v101, v101, v90, v91
	v_max3_f32 v100, v100, v89, v72
	v_max3_f32 v101, v101, v74, v75
	v_max3_f32 v100, v100, v73, v92
	v_max3_f32 v101, v101, v94, v95
	v_max3_f32 v100, v100, v93, v76
	v_max3_f32 v101, v101, v78, v79
	v_add_f32_e32 v196, v14, v15
	v_max3_f32 v14, v100, v77, v101
	v_mov_b32_e32 v15, v14
	s_nop 1
	v_permlane32_swap_b32_e32 v14, v15
	s_add_i32 s3, s16, s75
	s_mov_b32 s12, m0
	s_mov_b32 m0, s3
	s_nop 0
	global_load_lds_dwordx4 v[178:179], off
	s_mov_b32 m0, s12
	v_max_f32_e32 v14, v14, v15
	s_add_i32 s3, s78, s76
	s_mov_b32 s12, m0
	s_mov_b32 m0, s3
	s_nop 0
	global_load_lds_dwordx4 v[176:177], off
	s_mov_b32 m0, s12
	v_cmp_lt_f32_e32 vcc, s58, v14
	s_cmp_lg_u64 vcc, 0
	s_cselect_b64 s[12:13], -1, 0
	s_cbranch_vccnz .LBB0_574

; __device__ __forceinline__ unsigned xb_add(unsigned* p, unsigned v) { return __hip_atomic_fetch_add(p, v, __ATOMIC_RELAXED, __HIP_MEMORY_SCOPE_AGENT); }
; __device__ __forceinline__ void xcd_barrier(const XcdBarrier& b) {
;     asm volatile("s_waitcnt vmcnt(0)" ::: "memory");
;     __syncthreads();
;     if (threadIdx.x == 0) {
;         unsigned* bar = b.bar;
;         __builtin_amdgcn_s_waitcnt(0);
;         unsigned nloc = b.st[0], nx = b.st[1];
;         if (nloc == 0u) { xcd_barrier_complete(bar, b.x, nloc, nx); b.st[0] = nloc; b.st[1] = nx; }
;         const unsigned old = xb_add(&bar[XB_XSUB(b.x)], 1u);
;         const unsigned gen = old / nloc;
.LBB0_633:
	s_nop 0
	s_nop 0
	s_nop 0
	s_nop 0
	s_mov_b64 s[6:7], s[0:1]
	s_getreg_b32 s2, hwreg(HW_REG_XCC_ID, 0, 4)
	s_waitcnt vmcnt(0)
	s_barrier
	s_mov_b64 s[4:5], exec
	v_readlane_b32 s8, v255, 0
	v_readlane_b32 s9, v255, 1
	s_and_b64 s[8:9], s[4:5], s[8:9]
	v_readlane_b32 s41, v255, 10
	s_movk_i32 s42, 0x1000
	s_mov_b64 s[48:49], 0x1200
	s_mov_b32 s62, 0x3c800000
	s_mov_b64 exec, s[8:9]
	s_cbranch_execz .LBB0_685
	v_readlane_b32 s3, v255, 2
	s_load_dwordx2 s[6:7], s[6:7], 0x118
	s_waitcnt vmcnt(0) expcnt(0) lgkmcnt(0)
	v_mov_b32_e32 v0, s3
	ds_read_b32 v3, v0
	v_readlane_b32 s3, v255, 3
	s_and_b32 s2, s2, 15
	s_waitcnt lgkmcnt(0)
	v_cmp_ne_u32_e32 vcc, 0, v3
	v_mov_b32_e32 v0, s3
	ds_read_b32 v0, v0
	s_cbranch_vccnz .LBB0_649
	s_add_u32 s8, s6, 0x1000
	s_addc_u32 s9, s7, 0
	s_add_u32 s10, s6, 0x1100
	s_addc_u32 s11, s7, 0
	s_add_u32 s12, s6, 0x1200
	s_addc_u32 s13, s7, 0
	s_add_u32 s14, s6, 0x1300
	s_addc_u32 s15, s7, 0
	s_mov_b32 s3, 1
	s_branch .LBB0_637
